# GEMM phases: odd-slot waves return to s_setprio 1 (instead of 0) after each compute block, so the static priority asymmetry also holds during staging/epilogues
# speedup vs baseline: 1.0041x; 1.0030x over previous
.Ltail_20:
	s_getreg_b32 s98, hwreg(HW_REG_HW_ID, 0, 1)
	s_cmp_eq_u32 s98, 1
	s_cbranch_scc0 .Ltp_20
	s_setprio 1
